# S5 pass-2 items remapped so S5 prefix length complements the WG's GLA prefix length (P3 load balance)
# baseline (speedup 1.0000x reference)
; #define LAS __attribute__((address_space(3)))
; template <bool OUT>
; __device__ __forceinline__ void s5_pass(ldsp lds, const Params& p) {
;     const int tid = threadIdx.x, lane = tid & 63, w = tid >> 6, n = lane & 31, hi = lane >> 5;
;     LAS bf16_t* XT = (LAS bf16_t*)(lds + w * (32 * XP * 2));
;     const bf16_t* Ug = (const bf16_t*)(p.ws + WS_U); bf16_t* HB = (bf16_t*)(p.ws + WS_HB);
;     f32x2* S5E = (f32x2*)(p.ws + WS_S5E);
;     for (int item = blockIdx.x * 8 + w; item < 2048; item += gridDim.x * 8) {
;         const int b = item >> 9, g = (item >> 4) & 31, seg = item & 15;
;         if (!OUT && seg == 15) continue;
;         const float dt = expf(p.log_dt[g]);
;         float ar[2], ai[2]; bf16x8 Bf[4];
; #pragma unroll
;         for (int q = 0; q < 2; ++q) {
;             const int gp = g * 64 + n + 32 * q;
;             const float lr = p.lam_re[gp], li = p.lam_im[gp];
;             const float mag = expf(lr * dt); float sn, cs; sincosf(li * dt, &sn, &cs);
;             ar[q] = mag * cs; ai[q] = mag * sn;
;             const float den = lr * lr + li * li, am1 = ar[q] - 1.0f;
;             const float fre = (am1 * lr + ai[q] * li) / den, fim = (ai[q] * lr - am1 * li) / den;
;             const f32x4 br0 = *(const f32x4*)(p.b_re + (size_t)gp * 16 + 8 * hi), br1 = *(const f32x4*)(p.b_re + (size_t)gp * 16 + 8 * hi + 4);
;             const f32x4 bi0 = *(const f32x4*)(p.b_im + (size_t)gp * 16 + 8 * hi), bi1 = *(const f32x4*)(p.b_im + (size_t)gp * 16 + 8 * hi + 4);
;             const f32x4 vr0 = br0 * fre - bi0 * fim, vr1 = br1 * fre - bi1 * fim, vi0 = bi0 * fre + br0 * fim, vi1 = bi1 * fre + br1 * fim;
;             Bf[2 * q] = __builtin_bit_cast(bf16x8, pack8(vr0, vr1)); Bf[2 * q + 1] = __builtin_bit_cast(bf16x8, pack8(vi0, vi1));
;         }
;         float pwr[2][4], pwi[2][4];
.LBB0_448:
	s_and_b32 s0, s96, 15
	s_sub_u32 s0, 15, s0
	s_lshr_b32 s1, s96, 4
	s_lshl_b32 s1, s1, 7
	s_or_b32 s1, s1, s0
	s_lshl_b32 s0, s96, 3
	s_cmp_eq_u32 s62, 0x100
	s_cselect_b32 s1, s1, s0
	s_cselect_b32 s0, 4, 0
	v_lshlrev_b32_e32 v192, s0, v125
	v_add_u32_e32 v192, s1, v192
	s_movk_i32 s0, 0x800
	v_cmp_gt_i32_e32 vcc, s0, v192
	s_and_saveexec_b64 s[10:11], vcc
	s_cbranch_execz .LBB0_503
	v_mbcnt_lo_u32_b32 v1, -1, 0
	v_mbcnt_hi_u32_b32 v1, -1, v1
	v_readlane_b32 s80, v246, 6
	v_and_b32_e32 v3, 64, v1
	v_readlane_b32 s81, v246, 7
	s_movk_i32 s0, 0x2200
	v_xor_b32_e32 v2, 32, v1
	v_add_u32_e32 v3, 64, v3
	v_readlane_b32 s82, v246, 8
	v_readlane_b32 s83, v246, 9
	v_readlane_b32 s84, v246, 10
	v_readlane_b32 s85, v246, 11
	v_readlane_b32 s86, v246, 12
	v_readlane_b32 s87, v246, 13
	v_readlane_b32 s88, v246, 14
	v_readlane_b32 s89, v246, 15
	v_readlane_b32 s90, v246, 16
	v_readlane_b32 s91, v246, 17
	s_mov_b64 s[36:37], s[80:81]
	v_mad_i32_i24 v0, v125, s0, 0
	v_mov_b32_e32 v113, 0
	v_cmp_lt_i32_e32 vcc, v2, v3
	v_lshlrev_b32_e32 v112, 5, v137
	s_mov_b64 s[38:39], s[82:83]
	s_mov_b64 s[40:41], s[84:85]
	v_readlane_b32 s12, v246, 48
	v_cndmask_b32_e32 v1, v1, v2, vcc
	v_lshl_add_u32 v2, v120, 2, v0
	v_add_u32_e32 v3, v0, v122
	v_or_b32_e32 v0, 1, v121
	v_lshl_add_u64 v[116:117], s[38:39], 0, v[112:113]
	v_lshl_add_u64 v[118:119], s[40:41], 0, v[112:113]
	s_lshl_b32 s0, s96, 3
	v_lshlrev_b32_e32 v112, 3, v120
	v_readlane_b32 s13, v246, 49
	v_lshlrev_b32_e32 v195, 2, v1
	v_mul_u32_u24_e32 v6, 0x110, v0
	v_mov_b32_e32 v196, v192
	v_lshl_add_u64 v[0:1], s[12:13], 0, v[112:113]
	s_mov_b64 s[0:1], 0xa0000
	v_cmp_gt_u32_e64 s[2:3], 16, v120
	v_lshl_add_u64 v[124:125], v[0:1], 0, s[0:1]
	s_mov_b64 s[0:1], 0xa0100
	v_mov_b32_e32 v123, v113
	v_and_b32_e32 v193, 15, v220
	v_cndmask_b32_e64 v114, 0, 1.0, s[2:3]
	v_mul_u32_u24_e32 v4, 0x110, v120
	v_mul_u32_u24_e32 v5, 0x440, v137
	v_readlane_b32 s14, v246, 50
	v_readlane_b32 s15, v246, 51
	v_lshl_add_u64 v[126:127], v[0:1], 0, s[0:1]
	v_lshl_or_b32 v112, v137, 12, v139
	v_lshl_add_u64 v[0:1], s[12:13], 0, v[122:123]
	s_mov_b64 s[0:1], 0x1d340000
	v_lshlrev_b32_e32 v194, 6, v193
	v_cmp_eq_u32_e64 s[4:5], 0, v137
	s_lshl_b32 s18, s62, 3
	v_mov_b32_e32 v115, v114
	v_lshl_add_u64 v[128:129], s[12:13], 0, v[112:113]
	v_lshl_add_u64 v[122:123], v[0:1], 0, s[0:1]
	s_mov_b64 s[12:13], 0
	s_mov_b32 s19, 0x3fb8aa3b
	s_mov_b32 s20, 0xc2ce8ed0
	s_mov_b32 s21, 0x42b17218
	v_mov_b32_e32 v197, 0x7f800000
	s_brev_b32 s22, 18
	s_mov_b32 s23, 0xfe5163ab
	s_mov_b32 s24, 0x3c439041
	s_mov_b32 s25, 0xdb629599
	s_mov_b32 s26, 0xf534ddc0
	s_mov_b32 s27, 0xfc2757d1
	s_mov_b32 s28, 0x4e441529
	s_mov_b32 s29, 0xa2f9836e
	s_mov_b32 s30, 0x3fc90fda
	s_mov_b32 s31, 0x3f22f983
	s_mov_b32 s33, 0xbfc90fda
	v_mov_b32_e32 v198, 0x3c0881c4
	v_mov_b32_e32 v199, 0xbab64f3b
	s_movk_i32 s34, 0x1f8
	s_mov_b64 s[14:15], 0x200
	v_add_u32_e32 v200, v2, v5
	v_add_u32_e32 v201, v2, v6
	v_add_u32_e32 v202, v3, v4
	s_mov_b32 s35, 0x35342000
	s_mov_b32 s36, 0x35344000
	s_mov_b32 s37, 0x35346000
	s_movk_i32 s38, 0x7ff
	v_not_b32_e32 v203, 63
	v_not_b32_e32 v204, 31
	v_mov_b32_e32 v205, 0x7fc00000
	v_mov_b32_e32 v206, 0x800
	v_mov_b32_e32 v130, 2.0
	v_readlane_b32 s92, v246, 18
	v_readlane_b32 s93, v246, 19
	v_readlane_b32 s94, v246, 20
	v_readlane_b32 s95, v246, 21
	s_mov_b64 s[42:43], s[86:87]
	s_mov_b64 s[44:45], s[88:89]
	s_mov_b64 s[46:47], s[90:91]
	s_branch .LBB0_451
